# v112 + one static s_setprio 1 for waves 4-7 during the DSA phase (younger half of each SIMD pair)
# baseline (speedup 1.0000x reference)
; __global__ void __launch_bounds__(NWAVES * 64, 2) fwd_megakernel(Args args) {
;     ...
;                 for (int rep = 0; rep < REP_DSA; ++rep)
;                 if ((G & 7) == 0) { const int x = blockIdx.x & 7; const int nxw = (G >> 3) * NWAVES; const int wx = (blockIdx.x >> 3) * NWAVES + wave;
;                     for (int i = wx; i < 2 * SEQ; i += nxw) { const int combo = x + 8 * (i / SEQ);
;     ...
;  dsa_unit(QKV, SEL, AO, combo >> 2, combo & 3, i % SEQ, wl, lane);
;     ...
;  } }
.Ldsa_f0:
	s_waitcnt lgkmcnt(0)
	s_barrier
	ds_read_b32 v131, v132
	s_waitcnt lgkmcnt(0)
	v_readfirstlane_b32 s21, v131
	s_nop 3
	s_cmp_lt_u32 s0, 4
	s_cbranch_scc1 .Ldsa_prio_lo
	s_setprio 1
.Ldsa_prio_lo:
.Ldsa_run:
	s_cmpk_ge_u32 s21, 0x80
	s_cbranch_scc1 .Ldsa_done
	s_and_b32 s24, s1, 7
	s_and_b32 s25, s21, 1
	s_lshl_b32 s25, s25, 3
	s_add_u32 s24, s24, s25
	s_lshr_b32 s4, s24, 2
	s_lshl_b32 s4, s4, 12
	s_and_b32 s5, s24, 3
	s_lshr_b32 s6, s21, 1
	s_sub_u32 s6, 63, s6
	s_cmp_lg_u32 s0, 0
	s_cbranch_scc1 .Ldsa_f1
	v_mov_b32_e32 v133, 1
	s_mov_b64 exec, 1
	global_atomic_add v131, v183, v133, s[2:3] sc0
	s_mov_b64 exec, -1
